# diff attention: second V DMA piece uses inst offset:1024 with the first piece's m0 and address
# speedup vs baseline: 1.0013x; 1.0013x over previous
.LBB0_418:
	v_add_u32_e32 v225, s34, v192
	s_add_i32 s34, s30, 0x2000
	s_and_b32 s55, s34, 0x6000
	v_add_u32_e32 v114, s55, v191
	ds_read_b128 v[226:229], v114 offset:2560
	v_add_f32_e32 v86, v98, v99
	v_cvt_pk_bf16_f32 v126, v98, v99
	s_waitcnt lgkmcnt(1)
	v_mfma_f32_32x32x16_bf16 v[98:113], v[82:85], v[244:247], v[66:81]
	v_add_f32_e32 v86, v127, v86
	v_add_f32_e32 v86, v223, v86
	v_add_f32_e32 v86, v217, v86
	v_add_f32_e32 v86, v219, v86
	v_cvt_pk_bf16_f32 v127, v127, v223
	ds_read_b128 v[234:237], v114 offset:4096
	v_add_f32_e32 v82, v222, v86
	v_add_f32_e32 v82, v224, v82
	v_add_f32_e32 v82, v214, v82
	v_add_f32_e32 v115, v122, v82
	v_mfma_f32_32x32x16_bf16 v[82:97], v[134:137], v[244:247], v[66:81]
	v_cvt_pk_bf16_f32 v128, v217, v219
	v_cvt_pk_bf16_f32 v129, v222, v224
	ds_read_b128 v[134:137], v114 offset:4608
	s_waitcnt lgkmcnt(2)
	v_mfma_f32_32x32x16_bf16 v[98:113], v[130:133], v[248:251], v[98:113]
	v_add_f32_e32 v115, v123, v115
	v_add_f32_e32 v115, v220, v115
	v_add_f32_e32 v115, v216, v115
	v_add_f32_e32 v115, v218, v115
	v_cvt_pk_bf16_f32 v122, v214, v122
	v_cvt_pk_bf16_f32 v123, v123, v220
	ds_read_b128 v[130:133], v114 offset:6144
	v_mfma_f32_32x32x16_bf16 v[82:97], v[226:229], v[248:251], v[82:97]
	v_add_f32_e32 v115, v215, v115
	v_add_f32_e32 v115, v221, v115
	v_add_f32_e32 v115, v203, v115
	v_add_f32_e32 v115, v206, v115
	v_cvt_pk_bf16_f32 v124, v216, v218
	v_cvt_pk_bf16_f32 v125, v215, v221
	ds_read_b128 v[214:217], v114 offset:6656
	ds_read_b128 v[218:221], v201 offset:3072
	s_waitcnt lgkmcnt(3)
	v_mfma_f32_32x32x16_bf16 v[98:113], v[234:237], v[252:255], v[98:113]
	v_add_f32_e32 v114, v212, v115
	v_add_f32_e32 v114, v213, v114
	v_add_f32_e32 v114, v142, v114
	v_add_f32_e32 v114, v209, v114
	v_cvt_pk_bf16_f32 v118, v203, v206
	v_cvt_pk_bf16_f32 v119, v212, v213
	ds_read_b64_tr_b16 v[226:227], v225 offset:32768
	ds_read_b64_tr_b16 v[228:229], v225 offset:33280
	v_mfma_f32_32x32x16_bf16 v[82:97], v[134:137], v[252:255], v[82:97]
	v_add_f32_e32 v114, v204, v114
	v_add_f32_e32 v114, v207, v114
	v_add_f32_e32 v114, v144, v114
	v_add_f32_e32 v114, v202, v114
	v_cvt_pk_bf16_f32 v120, v142, v209
	v_cvt_pk_bf16_f32 v121, v204, v207
	ds_read_b64_tr_b16 v[134:135], v225 offset:36864
	ds_read_b64_tr_b16 v[136:137], v225 offset:37376
	s_waitcnt lgkmcnt(4)
	v_mfma_f32_32x32x16_bf16 v[98:113], v[130:133], v[218:221], v[98:113]
	v_add_f32_e32 v114, v205, v114
	v_add_f32_e32 v114, v210, v114
	v_add_f32_e32 v114, v143, v114
	v_add_f32_e32 v130, v145, v114
	v_cvt_pk_bf16_f32 v114, v144, v202
	v_cvt_pk_bf16_f32 v115, v205, v210
	ds_read_b64_tr_b16 v[138:139], v225 offset:40960
	ds_read_b64_tr_b16 v[140:141], v225 offset:41472
	v_mfma_f32_32x32x16_bf16 v[82:97], v[214:217], v[218:221], v[82:97]
	v_add_f32_e32 v116, v208, v130
	v_add_f32_e32 v130, v211, v116
	v_cvt_pk_bf16_f32 v116, v143, v145
	v_cvt_pk_bf16_f32 v117, v208, v211
	s_waitcnt lgkmcnt(4)
	v_mfma_f32_32x32x16_bf16 v[2:17], v[126:129], v[226:229], v[2:17]
	ds_read_b64_tr_b16 v[142:143], v225 offset:45056
	ds_read_b64_tr_b16 v[144:145], v225 offset:45568
	v_add_f32_e32 v202, v146, v130
	s_nop 2
	v_max3_f32 v130, v98, v99, v82
	v_max3_f32 v131, v100, v101, v83
	v_max3_f32 v130, v130, v84, v85
	v_max3_f32 v146, v130, v102, v103
	v_max3_f32 v203, v131, v104, v105
	s_waitcnt lgkmcnt(4)
	v_mfma_f32_32x32x16_bf16 v[50:65], v[126:129], v[134:137], v[50:65]
	ds_read_b64_tr_b16 v[130:131], v225 offset:33792
	ds_read_b64_tr_b16 v[132:133], v225 offset:34304
	s_add_i32 s34, s30, 0x8000
	s_and_b32 s34, s34, 0x6000
	v_lshl_add_u64 v[134:135], v[178:179], 0, s[30:31]
	s_add_i32 s34, s34, s89
	s_mov_b32 m0, s34
	s_nop 0
	global_load_lds_dwordx4 v[134:135], off
	v_max3_f32 v134, v146, v86, v87
	v_max3_f32 v135, v203, v88, v89
	v_max3_f32 v146, v134, v106, v107
	v_max3_f32 v203, v135, v108, v109
	s_waitcnt lgkmcnt(4)
	v_mfma_f32_32x32x16_bf16 v[34:49], v[126:129], v[138:141], v[34:49]
	s_movk_i32 s34, 0xc000
	s_mov_b32 s35, -1
	ds_read_b64_tr_b16 v[134:135], v225 offset:37888
	ds_read_b64_tr_b16 v[136:137], v225 offset:38400
	v_lshl_add_u64 v[138:139], v[180:181], 0, s[34:35]
	s_add_i32 s36, s2, s97
	s_mov_b32 m0, s36
	s_nop 0
	global_load_lds_dwordx4 v[138:139], off
	global_load_lds_dwordx4 v[138:139], off offset:1024
	v_max3_f32 v139, v203, v92, v93
	v_max3_f32 v146, v138, v110, v111
	v_max3_f32 v203, v139, v112, v113
	s_waitcnt lgkmcnt(4)
	v_mfma_f32_32x32x16_bf16 v[18:33], v[126:129], v[142:145], v[18:33]
	v_max3_f32 v126, v146, v94, v95
	v_max3_f32 v127, v203, v96, v97
	ds_read_b64_tr_b16 v[138:139], v225 offset:41984
	ds_read_b64_tr_b16 v[140:141], v225 offset:42496
	v_max_f32 v126, v126, v127
	s_nop 0
	v_mov_b32_e32 v127, v126
	s_nop 1
	v_permlane32_swap_b32_e32 v126, v127
	v_max_f32 v126, v126, v127
	s_nop 0
	v_cmp_lt_f32_e32 vcc, s49, v126
	s_cmp_lg_u64 vcc, 0
	s_cselect_b64 s[36:37], -1, 0
	s_cbranch_vccnz .LBB0_451

.LBB0_442:
	v_add_f32_e32 v146, v202, v130
	s_add_i32 s0, s2, 0x4000
	v_max3_f32 v130, v98, v99, v82
	s_cmpk_lg_u32 s2, 0x8000
	v_max3_f32 v131, v100, v101, v83
	v_max3_f32 v130, v130, v84, v85
	s_cselect_b32 s0, s0, 0
	v_max3_f32 v202, v130, v102, v103
	v_max3_f32 v203, v131, v104, v105
	s_waitcnt lgkmcnt(4)
	v_mfma_f32_32x32x16_bf16 v[50:65], v[126:129], v[138:141], v[50:65]
	ds_read_b64_tr_b16 v[130:131], v205 offset:33792
	ds_read_b64_tr_b16 v[132:133], v205 offset:34304
	v_lshl_add_u64 v[138:139], v[176:177], 0, s[30:31]
	v_lshl_add_u64 v[138:139], v[138:139], 0, s[18:19]
	s_add_i32 s31, s55, s89
	s_mov_b32 m0, s31
	s_nop 0
	global_load_lds_dwordx4 v[138:139], off
	v_max3_f32 v138, v202, v86, v87
	v_max3_f32 v139, v203, v88, v89
	v_max3_f32 v202, v138, v106, v107
	v_max3_f32 v203, v139, v108, v109
	s_waitcnt lgkmcnt(4)
	v_mfma_f32_32x32x16_bf16 v[34:49], v[126:129], v[142:145], v[34:49]
	ds_read_b64_tr_b16 v[138:139], v205 offset:37888
	ds_read_b64_tr_b16 v[140:141], v205 offset:38400
	s_add_i32 s31, s0, s97
	s_mov_b32 m0, s31
	s_nop 0
	global_load_lds_dwordx4 v[180:181], off
	global_load_lds_dwordx4 v[180:181], off offset:1024
	v_max3_f32 v142, v202, v90, v91
	v_max3_f32 v143, v203, v92, v93
	v_max3_f32 v202, v142, v110, v111
	v_max3_f32 v203, v143, v112, v113
	s_waitcnt lgkmcnt(4)
	v_mfma_f32_32x32x16_bf16 v[18:33], v[126:129], v[134:137], v[18:33]
	v_max3_f32 v126, v202, v94, v95
	v_max3_f32 v127, v203, v96, v97
	ds_read_b64_tr_b16 v[142:143], v205 offset:41984
	ds_read_b64_tr_b16 v[144:145], v205 offset:42496
	v_max_f32 v126, v126, v127
	s_nop 0
	v_mov_b32_e32 v127, v126
	s_nop 1
	v_permlane32_swap_b32_e32 v126, v127
	v_max_f32 v126, v126, v127
	s_nop 0
	v_cmp_lt_f32_e32 vcc, s49, v126
	s_cmp_lg_u64 vcc, 0
	s_cselect_b64 s[38:39], -1, 0
	s_cbranch_vccnz .LBB0_454
